# combo6 + GEMM phase prologue: all 14 staging pieces issued before the first wait (vmcnt 8 then 6)
# baseline (speedup 1.0000x reference)
.LBB0_79:
	s_add_u32 s60, s90, s8
	s_addc_u32 s61, s91, s9
	s_add_u32 s62, s90, s10
	s_addc_u32 s63, s91, s11
	s_add_i32 m0, s21, 0x18000
	v_lshl_add_u64 v[8:9], v[8:9], 0, s[30:31]
	s_nop 0
	global_load_lds_dwordx4 v[8:9], off
	v_lshl_add_u64 v[4:5], v[4:5], 0, s[30:31]
	s_add_i32 m0, s21, 0x1a000
	s_add_i32 s96, s21, 0x8000
	global_load_lds_dwordx4 v[4:5], off
	v_lshl_add_u64 v[4:5], v[6:7], 0, s[30:31]
	s_mov_b32 m0, s96
	s_add_i32 s97, s21, 0xa000
	global_load_lds_dwordx4 v[4:5], off
	v_lshl_add_u64 v[4:5], v[10:11], 0, s[30:31]
	s_mov_b32 m0, s97
	v_lshl_add_u64 v[2:3], v[2:3], 0, s[30:31]
	global_load_lds_dwordx4 v[4:5], off
	s_add_i32 m0, s21, 0x1c000
	v_lshl_add_u64 v[0:1], v[0:1], 0, s[30:31]
	global_load_lds_dwordx4 v[2:3], off
	s_add_i32 m0, s21, 0x1e000
	s_lshl_b32 s8, s41, 13
	global_load_lds_dwordx4 v[0:1], off
	s_waitcnt vmcnt(8)
	s_barrier
	v_lshlrev_b32_e32 v1, 2, v218
	v_lshl_or_b32 v0, v218, 6, v226
	v_and_b32_e32 v1, 32, v1
	s_lshr_b32 s80, s33, 6
	v_bitop3_b32 v0, v0, s8, v1 bitop3:0xde
	s_lshl_b32 s8, s39, 5
	s_and_b32 s8, s8, 0x60
	s_add_i32 s73, s80, -2
	s_cmpk_lt_u32 s38, 0x100
	s_cselect_b64 s[64:65], -1, 0
	s_lshl_b32 s76, s23, 3
	s_abs_i32 s86, s76
	v_cvt_f32_u32_e32 v1, s86
	v_lshl_or_b32 v229, s8, 7, v227
	v_or_b32_e32 v230, s8, v225
	s_sub_i32 s8, 0, s86
	v_rcp_iflag_f32_e32 v1, v1
	s_waitcnt vmcnt(6)
	s_lshr_b32 s94, s52, 3
	v_lshl_or_b32 v228, s41, 6, v218
	v_mul_f32_e32 v1, 0x4f7ffffe, v1
	v_cvt_u32_f32_e32 v1, v1
	s_ashr_i32 s87, s48, 31
	s_mov_b32 s53, s7
	s_and_b32 s95, s52, 7
	v_readfirstlane_b32 s9, v1
	s_mul_i32 s8, s8, s9
	s_mul_hi_u32 s8, s9, s8
	s_add_i32 s38, s94, 1
	s_bfe_i32 s39, s23, 0x1001c
	s_mov_b32 s23, 0
	s_add_i32 s41, s9, s8
	v_lshl_add_u64 v[186:187], s[6:7], 0, v[182:183]
	v_lshl_add_u64 v[188:189], s[6:7], 0, v[180:181]
	v_add_u32_e32 v231, 0, v0
	s_barrier
	s_branch .LBB0_82
